# team sync without L1 invalidate (no GO-region line can be in L1 since the last barrier invalidate)
# speedup vs baseline: 1.0323x; 1.0061x over previous
FUSE5_GOT:
	s_mov_b64 exec, s[70:71]
FUSE5_WAIT:
	s_barrier
	s_and_b32 s67, s73, 63
	s_lshr_b32 s68, s73, 6
	s_mul_i32 s67, s67, 48
	s_mul_i32 s68, s68, 6
	s_add_i32 s72, s67, s68
	s_lshl_b32 s35, s72, 2
	s_add_i32 s35, s35, 24
	s_mov_b32 s3, 1
	s_branch FUSE5_LN

FUSE11_GOT:
	s_mov_b64 exec, s[70:71]
FUSE11_WAIT:
	s_barrier
	s_and_b32 s67, s73, 63
	s_lshr_b32 s68, s73, 6
	s_mul_i32 s67, s67, 48
	s_mul_i32 s68, s68, 6
	s_add_i32 s72, s67, s68
	s_lshl_b32 s25, s72, 2
	s_add_i32 s25, s25, 24
	s_mov_b32 s3, 1
	s_branch FUSE11_LN

FUSE15_GOT:
	s_mov_b64 exec, s[70:71]
FUSE15_WAIT:
	s_barrier
	s_and_b32 s67, s73, 63
	s_lshr_b32 s68, s73, 6
	s_mul_i32 s67, s67, 48
	s_mul_i32 s68, s68, 6
	s_add_i32 s72, s67, s68
	s_lshl_b32 s19, s72, 2
	s_add_i32 s19, s19, 24
	s_mov_b32 s3, 1
	s_branch FUSE15_LN

FUSE20_GOT:
	s_mov_b64 exec, s[70:71]
FUSE20_WAIT:
	s_barrier
	s_and_b32 s67, s73, 63
	s_lshr_b32 s68, s73, 6
	s_mul_i32 s67, s67, 48
	s_mul_i32 s68, s68, 6
	s_add_i32 s72, s67, s68
	s_lshl_b32 s19, s72, 2
	v_add_u32_e32 v150, s19, v5
	s_add_i32 s19, s19, 24
	s_mov_b32 s17, 1
	s_mov_b64 s[6:7], 0
	s_mov_b64 s[2:3], 0
	s_branch FUSE20_LN
